# spin loops of the grid barriers and the row-statistics exchange poll without s_sleep (on top of the previous version)
# speedup vs baseline: 1.0037x; 1.0016x over previous
.LBB0_33:
	global_load_dword v17, v18, s[4:5] sc1
	global_load_dword v2, v18, s[6:7] sc1
	global_load_dword v3, v18, s[8:9] sc1
	global_load_dword v4, v18, s[12:13] sc1
	global_load_dword v5, v18, s[14:15] sc1
	global_load_dword v6, v18, s[16:17] sc1
	global_load_dword v7, v18, s[18:19] sc1
	global_load_dword v8, v18, s[20:21] sc1
	global_load_dword v9, v18, s[22:23] sc1
	global_load_dword v10, v18, s[24:25] sc1
	global_load_dword v11, v18, s[26:27] sc1
	global_load_dword v12, v18, s[28:29] sc1
	global_load_dword v13, v18, s[30:31] sc1
	global_load_dword v14, v18, s[34:35] sc1
	global_load_dword v15, v18, s[36:37] sc1
	global_load_dword v16, v18, s[38:39] sc1
	s_mov_b64 s[40:41], -1
	s_mov_b64 s[42:43], -1
	s_waitcnt vmcnt(14)
	v_add_u32_e32 v19, v2, v17
	s_waitcnt vmcnt(13)
	v_add_u32_e32 v19, v19, v3
	s_waitcnt vmcnt(12)
	v_add_u32_e32 v19, v19, v4
	s_waitcnt vmcnt(11)
	v_add_u32_e32 v19, v19, v5
	s_waitcnt vmcnt(10)
	v_add_u32_e32 v19, v19, v6
	s_waitcnt vmcnt(9)
	v_add_u32_e32 v19, v19, v7
	s_waitcnt vmcnt(8)
	v_add_u32_e32 v19, v19, v8
	s_waitcnt vmcnt(7)
	v_add_u32_e32 v19, v19, v9
	s_waitcnt vmcnt(6)
	v_add_u32_e32 v19, v19, v10
	s_waitcnt vmcnt(5)
	v_add_u32_e32 v19, v19, v11
	s_waitcnt vmcnt(4)
	v_add_u32_e32 v19, v19, v12
	s_waitcnt vmcnt(3)
	v_add_u32_e32 v19, v19, v13
	s_waitcnt vmcnt(2)
	v_add_u32_e32 v19, v19, v14
	s_waitcnt vmcnt(1)
	v_add_u32_e32 v19, v19, v15
	s_waitcnt vmcnt(0)
	v_add_u32_e32 v19, v19, v16
	v_cmp_eq_u32_e32 vcc, s33, v19
	s_cbranch_vccnz .LBB0_32
	s_and_b32 s40, s46, 0xff
	s_cmp_eq_u32 s40, 0
	s_mov_b64 s[40:41], -1
	s_mov_b64 s[44:45], -1
	s_nop 0
	s_cbranch_scc0 .LBB0_37
	global_load_dword v19, v18, s[2:3] sc1
	s_waitcnt vmcnt(0)
	v_cmp_eq_u32_e32 vcc, 0, v19
	s_cbranch_vccnz .LBB0_39
	s_mov_b64 s[44:45], 0

.LBB0_51:
	s_and_b32 s20, s24, 0xff
	s_mov_b64 s[18:19], -1
	s_cmp_lg_u32 s20, 0
	s_mov_b64 s[22:23], -1
	s_nop 0
	s_cbranch_scc1 .LBB0_54
	global_load_dword v4, v2, s[8:9] sc1
	s_waitcnt vmcnt(0)
	v_cmp_eq_u32_e32 vcc, 0, v4
	s_cbranch_vccnz .LBB0_56
	s_mov_b64 s[22:23], 0
	s_mov_b64 s[20:21], -1

.LBB0_68:
	s_and_b32 s18, s24, 0xff
	s_cmp_lg_u32 s18, 0
	s_mov_b64 s[20:21], -1
	s_nop 0
	s_cbranch_scc1 .LBB0_71
	global_load_dword v3, v2, s[8:9] sc1
	s_waitcnt vmcnt(0)
	v_cmp_eq_u32_e32 vcc, 0, v3
	s_cbranch_vccnz .LBB0_73
	s_mov_b64 s[20:21], 0
	s_mov_b64 s[18:19], -1

.LBB0_175:
	global_load_dword v17, v18, s[4:5] sc1
	global_load_dword v2, v18, s[6:7] sc1
	global_load_dword v3, v18, s[8:9] sc1
	global_load_dword v4, v18, s[10:11] sc1
	global_load_dword v5, v18, s[12:13] sc1
	global_load_dword v6, v18, s[14:15] sc1
	global_load_dword v7, v18, s[16:17] sc1
	global_load_dword v8, v18, s[18:19] sc1
	global_load_dword v9, v18, s[20:21] sc1
	global_load_dword v10, v18, s[22:23] sc1
	global_load_dword v11, v18, s[24:25] sc1
	global_load_dword v12, v18, s[26:27] sc1
	global_load_dword v13, v18, s[28:29] sc1
	global_load_dword v14, v18, s[30:31] sc1
	global_load_dword v15, v18, s[34:35] sc1
	global_load_dword v16, v18, s[36:37] sc1
	s_mov_b64 s[38:39], -1
	s_mov_b64 s[40:41], -1
	s_waitcnt vmcnt(14)
	v_add_u32_e32 v19, v2, v17
	s_waitcnt vmcnt(13)
	v_add_u32_e32 v19, v19, v3
	s_waitcnt vmcnt(12)
	v_add_u32_e32 v19, v19, v4
	s_waitcnt vmcnt(11)
	v_add_u32_e32 v19, v19, v5
	s_waitcnt vmcnt(10)
	v_add_u32_e32 v19, v19, v6
	s_waitcnt vmcnt(9)
	v_add_u32_e32 v19, v19, v7
	s_waitcnt vmcnt(8)
	v_add_u32_e32 v19, v19, v8
	s_waitcnt vmcnt(7)
	v_add_u32_e32 v19, v19, v9
	s_waitcnt vmcnt(6)
	v_add_u32_e32 v19, v19, v10
	s_waitcnt vmcnt(5)
	v_add_u32_e32 v19, v19, v11
	s_waitcnt vmcnt(4)
	v_add_u32_e32 v19, v19, v12
	s_waitcnt vmcnt(3)
	v_add_u32_e32 v19, v19, v13
	s_waitcnt vmcnt(2)
	v_add_u32_e32 v19, v19, v14
	s_waitcnt vmcnt(1)
	v_add_u32_e32 v19, v19, v15
	s_waitcnt vmcnt(0)
	v_add_u32_e32 v19, v19, v16
	v_cmp_eq_u32_e32 vcc, s33, v19
	s_cbranch_vccnz .LBB0_174
	s_and_b32 s38, s44, 0xff
	s_cmp_eq_u32 s38, 0
	s_mov_b64 s[38:39], -1
	s_mov_b64 s[42:43], -1
	s_nop 0
	s_cbranch_scc0 .LBB0_179
	global_load_dword v19, v18, s[2:3] sc1
	s_waitcnt vmcnt(0)
	v_cmp_eq_u32_e32 vcc, 0, v19
	s_cbranch_vccnz .LBB0_181
	s_mov_b64 s[42:43], 0

.LBB0_193:
	s_and_b32 s18, s22, 0xff
	s_mov_b64 s[16:17], -1
	s_cmp_lg_u32 s18, 0
	s_mov_b64 s[20:21], -1
	s_nop 0
	s_cbranch_scc1 .LBB0_196
	global_load_dword v4, v2, s[8:9] sc1
	s_waitcnt vmcnt(0)
	v_cmp_eq_u32_e32 vcc, 0, v4
	s_cbranch_vccnz .LBB0_198
	s_mov_b64 s[20:21], 0
	s_mov_b64 s[18:19], -1

.LBB0_211:
	s_and_b32 s16, s22, 0xff
	s_cmp_lg_u32 s16, 0
	s_mov_b64 s[18:19], -1
	s_nop 0
	s_cbranch_scc1 .LBB0_214
	global_load_dword v3, v2, s[8:9] sc1
	s_waitcnt vmcnt(0)
	v_cmp_eq_u32_e32 vcc, 0, v3
	s_cbranch_vccnz .LBB0_216
	s_mov_b64 s[18:19], 0
	s_mov_b64 s[16:17], -1

.LBB0_463:
	global_load_dword v17, v18, s[6:7] sc1
	global_load_dword v2, v18, s[8:9] sc1
	global_load_dword v3, v18, s[12:13] sc1
	global_load_dword v4, v18, s[14:15] sc1
	global_load_dword v5, v18, s[16:17] sc1
	global_load_dword v6, v18, s[18:19] sc1
	global_load_dword v7, v18, s[20:21] sc1
	global_load_dword v8, v18, s[22:23] sc1
	global_load_dword v9, v18, s[24:25] sc1
	global_load_dword v10, v18, s[26:27] sc1
	global_load_dword v11, v18, s[28:29] sc1
	global_load_dword v12, v18, s[30:31] sc1
	global_load_dword v13, v18, s[34:35] sc1
	global_load_dword v14, v18, s[36:37] sc1
	global_load_dword v15, v18, s[38:39] sc1
	global_load_dword v16, v18, s[40:41] sc1
	s_mov_b64 s[42:43], -1
	s_mov_b64 s[44:45], -1
	s_waitcnt vmcnt(14)
	v_add_u32_e32 v19, v2, v17
	s_waitcnt vmcnt(13)
	v_add_u32_e32 v19, v19, v3
	s_waitcnt vmcnt(12)
	v_add_u32_e32 v19, v19, v4
	s_waitcnt vmcnt(11)
	v_add_u32_e32 v19, v19, v5
	s_waitcnt vmcnt(10)
	v_add_u32_e32 v19, v19, v6
	s_waitcnt vmcnt(9)
	v_add_u32_e32 v19, v19, v7
	s_waitcnt vmcnt(8)
	v_add_u32_e32 v19, v19, v8
	s_waitcnt vmcnt(7)
	v_add_u32_e32 v19, v19, v9
	s_waitcnt vmcnt(6)
	v_add_u32_e32 v19, v19, v10
	s_waitcnt vmcnt(5)
	v_add_u32_e32 v19, v19, v11
	s_waitcnt vmcnt(4)
	v_add_u32_e32 v19, v19, v12
	s_waitcnt vmcnt(3)
	v_add_u32_e32 v19, v19, v13
	s_waitcnt vmcnt(2)
	v_add_u32_e32 v19, v19, v14
	s_waitcnt vmcnt(1)
	v_add_u32_e32 v19, v19, v15
	s_waitcnt vmcnt(0)
	v_add_u32_e32 v19, v19, v16
	v_cmp_eq_u32_e32 vcc, s33, v19
	s_cbranch_vccnz .LBB0_462
	s_and_b32 s42, s48, 0xff
	s_cmp_eq_u32 s42, 0
	s_mov_b64 s[42:43], -1
	s_mov_b64 s[46:47], -1
	s_nop 0
	s_cbranch_scc0 .LBB0_467
	global_load_dword v19, v18, s[2:3] sc1
	s_waitcnt vmcnt(0)
	v_cmp_eq_u32_e32 vcc, 0, v19
	s_cbranch_vccnz .LBB0_469
	s_mov_b64 s[46:47], 0

.LBB0_481:
	s_and_b32 s22, s26, 0xff
	s_mov_b64 s[20:21], -1
	s_cmp_lg_u32 s22, 0
	s_mov_b64 s[24:25], -1
	s_nop 0
	s_cbranch_scc1 .LBB0_484
	global_load_dword v4, v2, s[12:13] sc1
	s_waitcnt vmcnt(0)
	v_cmp_eq_u32_e32 vcc, 0, v4
	s_cbranch_vccnz .LBB0_486
	s_mov_b64 s[24:25], 0
	s_mov_b64 s[22:23], -1

.LBB0_498:
	s_and_b32 s20, s26, 0xff
	s_cmp_lg_u32 s20, 0
	s_mov_b64 s[22:23], -1
	s_nop 0
	s_cbranch_scc1 .LBB0_501
	global_load_dword v3, v2, s[12:13] sc1
	s_waitcnt vmcnt(0)
	v_cmp_eq_u32_e32 vcc, 0, v3
	s_cbranch_vccnz .LBB0_503
	s_mov_b64 s[22:23], 0
	s_mov_b64 s[20:21], -1

.LBB0_679:
	global_load_dword v133, v1, s[14:15] sc1
	s_mov_b64 s[16:17], -1
	s_mov_b64 s[18:19], -1
	s_waitcnt vmcnt(0)
	v_readfirstlane_b32 s9, v133
	s_cmp_gt_u32 s9, 31
	s_cbranch_scc1 .LBB0_678
	s_memrealtime s[16:17]
	s_waitcnt lgkmcnt(0)
	s_sub_u32 s16, s16, s10
	s_subb_u32 s17, s17, s11
	v_cmp_lt_u64_e32 vcc, s[16:17], v[130:131]
	s_cbranch_vccz .LBB0_677
	s_mov_b64 s[18:19], 0
	s_nop 0
	s_branch .LBB0_677
